# grid barrier: acquire's L1 invalidate issued right behind the arrival atomic, completes during the wait
# speedup vs baseline: 1.0060x; 1.0048x over previous
.LBB0_224:
	s_or_b64 exec, exec, s[6:7]
	buffer_inv sc1
	v_cvt_f32_u32_e32 v5, v3
	s_waitcnt vmcnt(1)
	v_readfirstlane_b32 s4, v4
	v_sub_u32_e32 v4, 0, v3
	v_rcp_iflag_f32_e32 v5, v5
	v_add_u32_e32 v6, s4, v2
	v_mul_f32_e32 v5, 0x4f7ffffe, v5
	v_cvt_u32_f32_e32 v5, v5
	v_mul_lo_u32 v2, v4, v5
	v_mul_hi_u32 v2, v5, v2
	v_add_u32_e32 v2, v5, v2
	v_mul_hi_u32 v2, v6, v2
	v_mul_lo_u32 v4, v2, v3
	v_sub_u32_e32 v4, v6, v4
	v_add_u32_e32 v5, 1, v2
	v_cmp_ge_u32_e32 vcc, v4, v3
	s_nop 1
	v_cndmask_b32_e32 v2, v2, v5, vcc
	v_sub_u32_e32 v5, v4, v3
	v_cndmask_b32_e32 v4, v4, v5, vcc
	v_add_u32_e32 v5, 1, v2
	v_cmp_ge_u32_e32 vcc, v4, v3
	v_add_u32_e32 v4, 1, v6
	s_nop 0
	v_cndmask_b32_e32 v2, v2, v5, vcc
	v_mul_lo_u32 v5, v3, v2
	v_add_u32_e32 v3, v5, v3
	v_cmp_ne_u32_e32 vcc, v4, v3
	s_and_saveexec_b64 s[4:5], vcc
	s_xor_b64 s[4:5], exec, s[4:5]
	s_cbranch_execz .LBB0_238
	s_waitcnt lgkmcnt(0)
	v_mov_b32_e32 v1, 0x2000
	global_load_dword v1, v1, s[2:3] offset:1024 sc1
	s_add_u32 s10, s2, 0x2400
	s_addc_u32 s11, s3, 0
	s_waitcnt vmcnt(0)
	v_cmp_eq_u32_e32 vcc, v1, v2
	s_and_saveexec_b64 s[6:7], vcc
	s_cbranch_execz .LBB0_237
	s_add_u32 s8, s96, 0x1200
	s_addc_u32 s9, s97, 0
	s_mov_b32 s22, 1
	s_mov_b64 s[12:13], 0
	v_mov_b32_e32 v1, 0
	s_branch .LBB0_228

.LBB0_237:
	s_or_b64 exec, exec, s[6:7]
	s_waitcnt vmcnt(0)
	s_waitcnt vmcnt(0)

.LBB0_255:
	s_or_b64 exec, exec, s[4:5]
	s_mov_b64 s[4:5], exec
	v_mbcnt_lo_u32_b32 v1, s4, 0
	v_mbcnt_hi_u32_b32 v1, s5, v1
	v_cmp_eq_u32_e32 vcc, 0, v1
	s_waitcnt vmcnt(0)
	s_and_saveexec_b64 s[6:7], vcc
	s_cbranch_execz .LBB0_257
	s_bcnt1_i32_b64 s4, s[4:5]
	v_mov_b32_e32 v1, 0x2000
	v_mov_b32_e32 v2, s4
	global_atomic_add v1, v2, s[2:3] offset:1024
.LBB0_257:
	s_or_b64 exec, exec, s[6:7]
	s_waitcnt vmcnt(0)

.LBB0_350:
	s_or_b64 exec, exec, s[4:5]
	s_mov_b64 s[4:5], exec
	v_mbcnt_lo_u32_b32 v1, s4, 0
	v_mbcnt_hi_u32_b32 v1, s5, v1
	v_cmp_eq_u32_e32 vcc, 0, v1
	s_waitcnt vmcnt(0)
	s_and_saveexec_b64 s[6:7], vcc
	s_cbranch_execz .LBB0_352
	s_bcnt1_i32_b64 s4, s[4:5]
	v_mov_b32_e32 v1, 0x2000
	v_mov_b32_e32 v2, s4
	global_atomic_add v1, v2, s[2:3] offset:1024
.LBB0_352:
	s_or_b64 exec, exec, s[6:7]
	s_waitcnt vmcnt(0)

.LBB0_476:
	s_or_b64 exec, exec, s[4:5]
	s_mov_b64 s[4:5], exec
	v_mbcnt_lo_u32_b32 v1, s4, 0
	v_mbcnt_hi_u32_b32 v1, s5, v1
	v_cmp_eq_u32_e32 vcc, 0, v1
	s_waitcnt vmcnt(0)
	s_and_saveexec_b64 s[6:7], vcc
	s_cbranch_execz .LBB0_478
	s_bcnt1_i32_b64 s4, s[4:5]
	v_mov_b32_e32 v1, 0x2000
	v_mov_b32_e32 v2, s4
	global_atomic_add v1, v2, s[2:3] offset:1024
.LBB0_478:
	s_or_b64 exec, exec, s[6:7]
	s_waitcnt vmcnt(0)

.LBB0_544:
	s_or_b64 exec, exec, s[4:5]
	s_mov_b64 s[4:5], exec
	v_mbcnt_lo_u32_b32 v1, s4, 0
	v_mbcnt_hi_u32_b32 v1, s5, v1
	v_cmp_eq_u32_e32 vcc, 0, v1
	s_waitcnt vmcnt(0)
	s_and_saveexec_b64 s[6:7], vcc
	s_cbranch_execz .LBB0_546
	s_bcnt1_i32_b64 s4, s[4:5]
	v_mov_b32_e32 v1, 0x2000
	v_mov_b32_e32 v2, s4
	global_atomic_add v1, v2, s[2:3] offset:1024
.LBB0_546:
	s_or_b64 exec, exec, s[6:7]
	s_waitcnt vmcnt(0)

.LBB0_744:
	s_or_b64 exec, exec, s[4:5]
	s_mov_b64 s[4:5], exec
	v_mbcnt_lo_u32_b32 v1, s4, 0
	v_mbcnt_hi_u32_b32 v1, s5, v1
	v_cmp_eq_u32_e32 vcc, 0, v1
	s_waitcnt vmcnt(0)
	s_and_saveexec_b64 s[6:7], vcc
	s_cbranch_execz .LBB0_746
	s_bcnt1_i32_b64 s4, s[4:5]
	v_mov_b32_e32 v1, 0x2000
	v_mov_b32_e32 v2, s4
	global_atomic_add v1, v2, s[2:3] offset:1024
.LBB0_746:
	s_or_b64 exec, exec, s[6:7]
	s_waitcnt vmcnt(0)
